# v78 = v72 + sb main tile loop: first K fragment of the next tile prefetched from LDS at the end of the current tile (v[248:251])
# baseline (speedup 1.0000x reference)
.LBB0_226:
	s_or_b64 exec, exec, s[12:13]
	s_lshl_b32 s0, s5, 8
	s_and_b32 s0, s0, 0xf00
	ds_read_b128 v[64:67], v221
	ds_read_b128 v[68:71], v221 offset:64
	ds_read_b128 v[76:79], v221 offset:2304
	ds_read_b128 v[80:83], v221 offset:2368
	v_or_b32_e32 v101, v168, v122
	v_or_b32_e32 v116, 3, v101
	v_cmp_lt_u32_e64 s[28:29], v116, v100
	v_or_b32_e32 v102, 16, v100
	v_cmp_lt_u32_e64 s[12:13], v101, v102
	v_cmp_lt_u32_e64 s[14:15], v116, v102
	s_waitcnt lgkmcnt(3)
	v_mfma_f32_16x16x32_bf16 v[72:75], v[64:67], v[48:51], 0
	s_waitcnt lgkmcnt(1)
	v_mfma_f32_16x16x32_bf16 v[84:87], v[76:79], v[48:51], 0
	v_mfma_f32_16x16x32_bf16 v[88:91], v[76:79], v[52:55], 0
	v_mfma_f32_16x16x32_bf16 v[72:75], v[68:71], v[56:59], v[72:75]
	v_mfma_f32_16x16x32_bf16 v[64:67], v[64:67], v[52:55], 0
	s_waitcnt lgkmcnt(0)
	v_mfma_f32_16x16x32_bf16 v[76:79], v[80:83], v[56:59], v[84:87]
	s_nop 4
	v_mul_f32_e64 v92, |v75|, s51
	v_mfma_f32_16x16x32_bf16 v[80:83], v[80:83], v[60:63], v[88:91]
	v_max_f32_e32 v113, 0, v73
	v_max_f32_e32 v84, v72, v72
	s_nop 0
	v_mul_f32_e64 v88, |v73|, s51
	v_mfma_f32_16x16x32_bf16 v[68:71], v[68:71], v[60:63], v[64:67]
	v_exp_f32_e32 v87, v88
	v_max_f32_e32 v104, v76, v76
	v_mul_f32_e64 v110, |v79|, s51
	v_max_f32_e32 v89, v74, v74
	v_add_f32_e32 v87, 1.0, v87
	s_nop 2
	v_max_f32_e32 v97, v70, v70
	v_mul_f32_e64 v90, |v74|, s51
	v_max_f32_e32 v91, v75, v75
	v_max_f32_e32 v93, v68, v68
	v_mul_f32_e64 v94, |v68|, s51
	v_mul_f32_e64 v96, |v69|, s51
	v_mul_f32_e64 v98, |v70|, s51
	v_mul_f32_e64 v107, |v77|, s51
	v_max_f32_e32 v111, 0, v84
	v_max_f32_e32 v84, 0, v97
	v_max_f32_e32 v97, 0, v104
	v_exp_f32_e32 v104, v110
	v_log_f32_e32 v87, v87
	v_mul_f32_e64 v105, |v76|, s51
	v_max_f32_e32 v114, 0, v89
	v_exp_f32_e32 v89, v90
	v_max_f32_e32 v115, 0, v91
	v_exp_f32_e32 v90, v92
	v_max_f32_e32 v92, 0, v93
	v_exp_f32_e32 v91, v94
	v_exp_f32_e32 v93, v96
	v_exp_f32_e32 v94, v98
	v_exp_f32_e32 v98, v107
	v_exp_f32_e32 v96, v105
	v_fmac_f32_e32 v113, 0x3f317218, v87
	v_add_f32_e32 v87, 1.0, v104
	v_mul_f32_e64 v103, |v71|, s51
	v_add_f32_e32 v93, 1.0, v93
	v_add_f32_e32 v107, 1.0, v98
	v_log_f32_e32 v87, v87
	v_or_b32_e32 v85, 16, v101
	v_max_f32_e32 v88, 0, v69
	v_exp_f32_e32 v95, v103
	v_max_f32_e32 v103, 0, v77
	v_add_f32_e32 v106, 1.0, v96
	v_log_f32_e32 v96, v93
	v_log_f32_e32 v93, v107
	v_cmp_lt_u32_e32 vcc, v85, v100
	v_mul_f32_e64 v86, |v72|, s51
	v_mul_f32_e64 v109, |v78|, s51
	v_max_f32_e32 v104, 0, v79
	v_mul_f32_e64 v85, |v80|, s51
	v_exp_f32_e32 v112, v86
	v_max_f32_e32 v86, 0, v71
	v_exp_f32_e32 v99, v109
	v_exp_f32_e32 v85, v85
	v_fmac_f32_e32 v104, 0x3f317218, v87
	v_add_f32_e32 v89, 1.0, v89
	v_fmac_f32_e32 v103, 0x3f317218, v93
	v_max_f32_e32 v93, 0, v80
	v_mul_f32_e64 v87, |v81|, s51
	v_add_f32_e32 v91, 1.0, v91
	v_log_f32_e32 v89, v89
	v_exp_f32_e32 v87, v87
	v_log_f32_e32 v98, v91
	v_log_f32_e32 v91, v106
	v_add_f32_e32 v90, 1.0, v90
	v_add_f32_e32 v94, 1.0, v94
	v_add_f32_e32 v95, 1.0, v95
	v_add_f32_e32 v99, 1.0, v99
	v_add_f32_e32 v85, 1.0, v85
	v_log_f32_e32 v109, v90
	v_log_f32_e32 v90, v94
	v_log_f32_e32 v94, v95
	v_log_f32_e32 v95, v99
	v_log_f32_e32 v99, v85
	v_fmac_f32_e32 v114, 0x3f317218, v89
	v_max_f32_e32 v89, 0, v81
	v_add_f32_e32 v85, 1.0, v87
	v_mul_f32_e64 v87, |v82|, s51
	v_fmac_f32_e32 v97, 0x3f317218, v91
	v_exp_f32_e32 v91, v87
	v_cndmask_b32_e64 v106, 0, -v97, vcc
	v_log_f32_e32 v97, v85
	v_add_f32_e32 v105, 1.0, v112
	v_max_f32_e32 v87, 0, v82
	v_add_f32_e32 v85, 1.0, v91
	v_mul_f32_e64 v91, |v83|, s51
	v_log_f32_e32 v105, v105
	v_exp_f32_e32 v91, v91
	v_fmac_f32_e32 v115, 0x3f317218, v109
	v_or_b32_e32 v109, 1, v101
	v_or_b32_e32 v112, 2, v101
	v_fmac_f32_e32 v111, 0x3f317218, v105
	v_max_f32_e32 v107, 0, v78
	v_add_f32_e32 v91, 1.0, v91
	v_cmp_lt_u32_e64 s[36:37], v109, v100
	v_cmp_lt_u32_e64 s[26:27], v112, v100
	v_cndmask_b32_e64 v105, 0, -v111, s[10:11]
	v_fmac_f32_e32 v107, 0x3f317218, v95
	v_log_f32_e32 v95, v85
	v_log_f32_e32 v91, v91
	v_cndmask_b32_e64 v110, 0, -v113, s[36:37]
	v_or_b32_e32 v111, 19, v101
	v_cndmask_b32_e64 v113, 0, -v114, s[26:27]
	v_or_b32_e32 v114, 18, v101
	v_or_b32_e32 v108, 17, v101
	v_cmp_lt_u32_e64 s[30:31], v114, v100
	v_cmp_lt_u32_e64 s[34:35], v111, v100
	v_cndmask_b32_e64 v115, 0, -v115, s[28:29]
	v_cmp_lt_u32_e64 s[38:39], v108, v100
	v_cndmask_b32_e64 v107, 0, -v107, s[30:31]
	v_cndmask_b32_e64 v100, 0, -v104, s[34:35]
	v_max_f32_e32 v85, 0, v83
	v_cndmask_b32_e64 v103, 0, -v103, s[38:39]
	v_pk_fma_f32 v[92:93], v[98:99], s[62:63], v[92:93] op_sel_hi:[1,0,1]
	v_cmp_lt_u32_e64 s[18:19], v108, v102
	v_cmp_lt_u32_e64 s[20:21], v109, v102
	v_cmp_lt_u32_e64 s[16:17], v114, v102
	v_cmp_lt_u32_e64 s[22:23], v111, v102
	v_cmp_lt_u32_e64 s[24:25], v112, v102
	v_add_f32_e32 v98, v115, v113
	v_add_f32_e32 v102, v100, v107
	v_pk_fma_f32 v[86:87], v[94:95], s[62:63], v[86:87] op_sel_hi:[1,0,1]
	v_pk_fma_f32 v[84:85], v[90:91], s[62:63], v[84:85] op_sel_hi:[1,0,1]
	v_add_f32_e32 v99, v110, v98
	v_add_f32_e32 v103, v103, v102
	v_pk_fma_f32 v[88:89], v[96:97], s[62:63], v[88:89] op_sel_hi:[1,0,1]
	v_cndmask_b32_e64 v87, 0, -v87, s[16:17]
	v_cndmask_b32_e64 v86, 0, -v86, s[14:15]
	v_cndmask_b32_e64 v85, 0, -v85, s[22:23]
	v_cndmask_b32_e64 v84, 0, -v84, s[24:25]
	v_add_f32_e32 v101, v105, v99
	v_add_f32_e32 v105, v106, v103
	v_cndmask_b32_e64 v89, 0, -v89, s[18:19]
	v_cndmask_b32_e64 v88, 0, -v88, s[20:21]
	v_pk_add_f32 v[90:91], v[84:85], v[86:87]
	v_mov_b32_e32 v84, v101
	v_mov_b32_e32 v87, v101
	v_mov_b32_e32 v94, v105
	v_mov_b32_e32 v95, v105
	v_cndmask_b32_e64 v93, 0, -v93, s[10:11]
	v_cndmask_b32_e64 v92, 0, -v92, s[12:13]
	v_pk_add_f32 v[88:89], v[88:89], v[90:91]
	v_permlane16_swap_b32_e32 v84, v87
	v_permlane16_swap_b32_e32 v94, v95
	v_pk_add_f32 v[92:93], v[92:93], v[88:89]
	v_cndmask_b32_e64 v84, v84, v87, s[8:9]
	v_cndmask_b32_e64 v94, v94, v95, s[8:9]
	v_add_f32_e32 v108, v101, v84
	v_mov_b32_e32 v84, v92
	v_mov_b32_e32 v87, v92
	v_add_f32_e32 v106, v105, v94
	v_mov_b32_e32 v94, v93
	v_mov_b32_e32 v95, v93
	v_permlane16_swap_b32_e32 v84, v87
	s_nop 0
	v_permlane16_swap_b32_e32 v94, v95
	v_cndmask_b32_e64 v95, v94, v95, s[8:9]
	v_cndmask_b32_e64 v94, v84, v87, s[8:9]
	v_mov_b32_e32 v84, v108
	v_mov_b32_e32 v87, v108
	v_mov_b32_e32 v96, v106
	v_mov_b32_e32 v97, v106
	v_pk_add_f32 v[94:95], v[92:93], v[94:95]
	v_permlane32_swap_b32_e32 v84, v87
	v_permlane32_swap_b32_e32 v96, v97
	v_cndmask_b32_e64 v109, v84, v87, s[6:7]
	v_mov_b32_e32 v84, v94
	v_mov_b32_e32 v87, v94
	v_cndmask_b32_e64 v107, v96, v97, s[6:7]
	v_mov_b32_e32 v96, v95
	v_mov_b32_e32 v97, v95
	v_permlane32_swap_b32_e32 v84, v87
	s_nop 0
	v_permlane32_swap_b32_e32 v96, v97
	v_add_f32_e32 v104, v106, v107
	v_cndmask_b32_e64 v97, v96, v97, s[6:7]
	v_cndmask_b32_e64 v96, v84, v87, s[6:7]
	v_sub_f32_e32 v84, v106, v105
	v_add_f32_e32 v87, 0, v104
	v_sub_f32_e32 v106, v108, v101
	v_fmac_f32_e32 v87, v208, v106
	v_fmac_f32_e32 v87, v209, v109
	v_add_f32_e32 v72, v72, v87
	v_add_f32_e32 v73, v73, v87
	v_add_f32_e32 v72, v101, v72
	v_add_f32_e32 v73, v99, v73
	v_mul_f32_e32 v72, 0x3fb8aa3b, v72
	v_mul_f32_e32 v73, 0x3fb8aa3b, v73
	v_exp_f32_e32 v72, v72
	v_exp_f32_e32 v73, v73
	v_fma_f32 v84, v208, v84, 0
	v_fmac_f32_e32 v84, v209, v107
	v_cndmask_b32_e64 v99, 0, v72, s[10:11]
	v_cndmask_b32_e64 v101, 0, v73, s[36:37]
	v_add_f32_e32 v72, v78, v84
	v_add_f32_e32 v73, v74, v87
	v_add_f32_e32 v72, v102, v72
	v_add_f32_e32 v73, v98, v73
	v_mul_f32_e32 v72, 0x3fb8aa3b, v72
	v_mul_f32_e32 v73, 0x3fb8aa3b, v73
	v_exp_f32_e32 v72, v72
	v_exp_f32_e32 v73, v73
	v_add_f32_e32 v74, v79, v84
	v_pk_add_f32 v[106:107], v[94:95], v[96:97]
	v_cndmask_b32_e64 v78, 0, v72, s[30:31]
	v_cndmask_b32_e64 v79, 0, v73, s[26:27]
	v_pk_add_f32 v[72:73], v[94:95], v[92:93] neg_lo:[0,1] neg_hi:[0,1]
	v_add_f32_e32 v76, v76, v84
	v_fma_f32 v73, v208, v73, 0
	v_add_f32_e32 v77, v77, v84
	v_fmac_f32_e32 v73, v209, v97
	v_add_f32_e32 v84, 0, v107
	v_fmac_f32_e32 v84, v208, v72
	v_add_f32_e32 v72, v80, v73
	v_add_f32_e32 v80, v81, v73
	v_add_f32_e32 v80, v89, v80
	v_mul_f32_e32 v80, 0x3fb8aa3b, v80
	v_exp_f32_e32 v80, v80
	v_fmac_f32_e32 v84, v209, v96
	ds_read2_b64 v[64:67], v222 offset0:32 offset1:36
	v_add_f32_e32 v75, v75, v87
	v_add_f32_e32 v68, v68, v84
	v_add_f32_e32 v69, v69, v84
	v_cndmask_b32_e64 v87, 0, v80, s[18:19]
	v_add_f32_e32 v80, v82, v73
	v_add_f32_e32 v70, v70, v84
	v_add_f32_e32 v73, v83, v73
	v_add_f32_e32 v71, v71, v84
	v_add_f32_e32 v76, v105, v76
	v_add_f32_e32 v77, v103, v77
	v_add_f32_e32 v74, v100, v74
	v_add_f32_e32 v75, v115, v75
	v_add_f32_e32 v72, v93, v72
	v_add_f32_e32 v68, v92, v68
	v_add_f32_e32 v69, v88, v69
	v_add_f32_e32 v80, v91, v80
	v_add_f32_e32 v70, v90, v70
	v_add_f32_e32 v73, v85, v73
	v_add_f32_e32 v71, v86, v71
	v_mul_f32_e32 v76, 0x3fb8aa3b, v76
	v_mul_f32_e32 v77, 0x3fb8aa3b, v77
	v_mul_f32_e32 v74, 0x3fb8aa3b, v74
	v_mul_f32_e32 v75, 0x3fb8aa3b, v75
	v_mul_f32_e32 v72, 0x3fb8aa3b, v72
	v_mul_f32_e32 v68, 0x3fb8aa3b, v68
	v_mul_f32_e32 v69, 0x3fb8aa3b, v69
	v_mul_f32_e32 v80, 0x3fb8aa3b, v80
	v_mul_f32_e32 v70, 0x3fb8aa3b, v70
	v_mul_f32_e32 v73, 0x3fb8aa3b, v73
	v_mul_f32_e32 v71, 0x3fb8aa3b, v71
	v_exp_f32_e32 v76, v76
	v_exp_f32_e32 v77, v77
	v_exp_f32_e32 v74, v74
	v_exp_f32_e32 v75, v75
	v_exp_f32_e32 v72, v72
	v_exp_f32_e32 v68, v68
	v_exp_f32_e32 v69, v69
	v_exp_f32_e32 v80, v80
	v_exp_f32_e32 v70, v70
	v_exp_f32_e32 v73, v73
	v_exp_f32_e32 v71, v71
	v_cndmask_b32_e32 v76, 0, v76, vcc
	v_cndmask_b32_e64 v77, 0, v77, s[38:39]
	v_cndmask_b32_e64 v74, 0, v74, s[34:35]
	v_cndmask_b32_e64 v75, 0, v75, s[28:29]
	v_cndmask_b32_e64 v72, 0, v72, s[10:11]
	v_cndmask_b32_e64 v68, 0, v68, s[12:13]
	v_cndmask_b32_e64 v69, 0, v69, s[20:21]
	v_cndmask_b32_e64 v84, 0, v80, s[16:17]
	v_cndmask_b32_e64 v70, 0, v70, s[24:25]
	v_cndmask_b32_e64 v73, 0, v73, s[22:23]
	v_cndmask_b32_e64 v71, 0, v71, s[14:15]
	v_cvt_pk_bf16_f32 v80, v99, v101
	v_cvt_pk_bf16_f32 v81, v79, v75
	v_cvt_pk_bf16_f32 v82, v76, v77
	v_cvt_pk_bf16_f32 v83, v78, v74
	v_cvt_pk_bf16_f32 v96, v68, v69
	v_cvt_pk_bf16_f32 v97, v70, v71
	v_cvt_pk_bf16_f32 v98, v72, v87
	v_cvt_pk_bf16_f32 v99, v84, v73
	s_waitcnt lgkmcnt(0)
	v_mfma_f32_16x16x32_bf16 v[92:95], v[64:67], v[80:83], 0
	ds_read2_b64 v[100:103], v212 offset1:4
	s_add_i32 s14, s0, 0xffffff80
	s_cmp_eq_u32 s0, 0
	v_mfma_f32_16x16x32_bf16 v[76:79], v[64:67], v[96:99], 0
	ds_read2_b64 v[64:67], v210 offset1:4
	s_cselect_b64 s[12:13], -1, 0
	v_mov_b32_e32 v105, v107
	s_waitcnt lgkmcnt(0)
	v_mfma_f32_16x16x32_bf16 v[88:91], v[64:67], v[80:83], 0
	s_and_b64 s[0:1], s[12:13], exec
	s_cselect_b32 s22, 0, s14
	v_mfma_f32_16x16x32_bf16 v[72:75], v[64:67], v[96:99], 0
	ds_read2_b64 v[64:67], v211 offset1:4
	s_waitcnt lgkmcnt(0)
	v_mfma_f32_16x16x32_bf16 v[84:87], v[64:67], v[80:83], 0
	v_mfma_f32_16x16x32_bf16 v[68:71], v[64:67], v[96:99], 0
	v_add_f32_e32 v64, v108, v109
	v_mov_b32_e32 v65, v106
	v_pk_add_f32 v[104:105], v[64:65], v[104:105]
	v_mfma_f32_16x16x32_bf16 v[80:83], v[100:103], v[80:83], 0
	v_cmp_gt_f32_e32 vcc, s63, v104
	v_cmp_gt_f32_e64 s[0:1], s63, v105
	s_and_b64 s[0:1], vcc, s[0:1]
	v_mfma_f32_16x16x32_bf16 v[64:67], v[100:103], v[96:99], 0
	v_cndmask_b32_e64 v96, 0, 1, s[0:1]
	v_cmp_ne_u32_e32 vcc, 0, v96
	v_pk_add_f32 v[170:171], v[104:105], 0 op_sel_hi:[1,0]
	s_cmp_eq_u64 vcc, exec
	s_mov_b64 s[0:1], -1
	s_cbranch_scc1 .LBB0_232
	v_cmp_lt_i32_e32 vcc, s22, v168
	s_mov_b64 s[0:1], 0
	s_and_saveexec_b64 s[14:15], vcc
	s_cbranch_execz .LBB0_231
	s_and_b32 s0, s33, 0xf00
	v_add_u32_e32 v112, s0, v213
	s_mov_b64 s[16:17], 0
	v_mov_b32_e32 v113, v214
	ds_read_b128 v[248:251], v113
	v_mov_b32_e32 v114, v125
.LBB0_229:
	v_add_u32_e32 v96, 0, v113
	ds_read_b128 v[172:175], v96 offset:64
	ds_read_b128 v[224:227], v96 offset:2304
	ds_read_b128 v[228:231], v96 offset:2368
	v_add_u32_e32 v110, 0, v114
	s_waitcnt lgkmcnt(3)
	v_mfma_f32_16x16x32_bf16 v[232:235], v[248:251], v[48:51], 0
	v_add_u32_e32 v96, 0xd800, v110
	ds_read2_b64 v[100:103], v96 offset0:24 offset1:28
	v_add_u32_e32 v96, 0x109c0, v110
	s_waitcnt lgkmcnt(3)
	v_mfma_f32_16x16x32_bf16 v[232:235], v[172:175], v[56:59], v[232:235]
	v_add_u32_e32 v98, 0x109e0, v110
	ds_read_b64 v[96:97], v96
	ds_read_b64 v[98:99], v98
	v_mfma_f32_16x16x32_bf16 v[116:119], v[248:251], v[52:55], 0
	v_add_u32_e32 v104, 0x13ac0, v110
	s_nop 2
	v_mul_f32_e64 v132, |v232|, s51
	v_exp_f32_e32 v132, v132
	v_mul_f32_e64 v141, |v233|, s51
	v_exp_f32_e32 v141, v141
	v_mul_f32_e64 v143, |v234|, s51
	v_add_f32_e32 v132, 1.0, v132
	v_exp_f32_e32 v143, v143
	v_log_f32_e32 v132, v132
	v_mul_f32_e64 v149, |v235|, s51
	v_add_f32_e32 v141, 1.0, v141
	v_exp_f32_e32 v149, v149
	v_log_f32_e32 v141, v141
	v_max_f32_e32 v115, 0, v232
	v_add_f32_e32 v143, 1.0, v143
	v_fmac_f32_e32 v115, 0x3f317218, v132
	v_log_f32_e32 v143, v143
	v_max_f32_e32 v132, 0, v233
	v_add_f32_e32 v149, 1.0, v149
	v_mfma_f32_16x16x32_bf16 v[116:119], v[172:175], v[60:63], v[116:119]
	v_fmac_f32_e32 v132, 0x3f317218, v141
	v_log_f32_e32 v149, v149
	v_max_f32_e32 v141, 0, v234
	v_fmac_f32_e32 v141, 0x3f317218, v143
	v_max_f32_e32 v143, 0, v235
	v_fmac_f32_e32 v143, 0x3f317218, v149
	s_nop 1
	v_max_f32_e32 v176, 0, v116
	v_mul_f32_e64 v149, |v116|, s51
	v_exp_f32_e32 v149, v149
	s_waitcnt lgkmcnt(4)
	v_mfma_f32_16x16x32_bf16 v[236:239], v[224:227], v[48:51], 0
	v_sub_f32_e64 v141, -v141, v143
	v_sub_f32_e32 v132, v141, v132
	v_add_f32_e32 v149, 1.0, v149
	v_mfma_f32_16x16x32_bf16 v[224:227], v[224:227], v[52:55], 0
	v_sub_f32_e32 v115, v132, v115
	v_mov_b32_e32 v159, v115
	v_add_u32_e32 v106, 0x13ae0, v110
	s_waitcnt lgkmcnt(3)
	v_mfma_f32_16x16x32_bf16 v[172:175], v[228:231], v[56:59], v[236:239]
	v_add_u32_e32 v108, 0x16bc0, v110
	v_add_u32_e32 v110, 0x16be0, v110
	ds_read_b64 v[104:105], v104
	ds_read_b64 v[106:107], v106
	v_mfma_f32_16x16x32_bf16 v[224:227], v[228:231], v[60:63], v[224:227]
	v_log_f32_e32 v228, v149
	v_max_f32_e32 v230, 0, v117
	v_mul_f32_e64 v149, |v117|, s51
	v_exp_f32_e32 v149, v149
	v_mul_f32_e64 v151, |v172|, s51
	v_exp_f32_e32 v151, v151
	v_mul_f32_e64 v153, |v173|, s51
	v_add_f32_e32 v149, 1.0, v149
	v_log_f32_e32 v236, v149
	v_max_f32_e32 v238, 0, v118
	v_mul_f32_e64 v149, |v118|, s51
	v_exp_f32_e32 v149, v149
	v_exp_f32_e32 v153, v153
	v_mul_f32_e64 v155, |v174|, s51
	v_add_f32_e32 v151, 1.0, v151
	v_add_f32_e32 v149, 1.0, v149
	v_log_f32_e32 v240, v149
	v_max_f32_e32 v242, 0, v119
	v_mul_f32_e64 v149, |v119|, s51
	v_exp_f32_e32 v149, v149
	v_exp_f32_e32 v155, v155
	v_log_f32_e32 v151, v151
	v_mul_f32_e64 v157, |v175|, s51
	v_add_f32_e32 v149, 1.0, v149
	v_add_f32_e32 v153, 1.0, v153
	v_exp_f32_e32 v157, v157
	v_log_f32_e32 v244, v149
	v_log_f32_e32 v153, v153
	v_max_f32_e32 v149, 0, v172
	v_add_f32_e32 v155, 1.0, v155
	v_fmac_f32_e32 v149, 0x3f317218, v151
	v_log_f32_e32 v155, v155
	v_max_f32_e32 v151, 0, v173
	v_add_f32_e32 v157, 1.0, v157
	v_fmac_f32_e32 v151, 0x3f317218, v153
	v_log_f32_e32 v157, v157
	v_max_f32_e32 v153, 0, v174
	v_fmac_f32_e32 v153, 0x3f317218, v155
	v_max_f32_e32 v155, 0, v175
	v_fmac_f32_e32 v155, 0x3f317218, v157
	v_max_f32_e32 v177, 0, v224
	v_mul_f32_e64 v157, |v224|, s51
	v_exp_f32_e32 v157, v157
	v_sub_f32_e64 v153, -v153, v155
	v_sub_f32_e32 v151, v153, v151
	v_sub_f32_e32 v149, v151, v149
	v_add_f32_e32 v157, 1.0, v157
	v_log_f32_e32 v229, v157
	v_max_f32_e32 v231, 0, v225
	v_mul_f32_e64 v157, |v225|, s51
	v_exp_f32_e32 v157, v157
	v_mov_b32_e32 v161, v149
	ds_read_b64 v[108:109], v108
	ds_read_b64 v[110:111], v110
	v_add_f32_e32 v157, 1.0, v157
	v_log_f32_e32 v237, v157
	v_max_f32_e32 v239, 0, v226
	v_mul_f32_e64 v157, |v226|, s51
	v_exp_f32_e32 v157, v157
	v_subrev_u32_e32 v114, 64, v114
	v_add_u32_e32 v113, 0xffffee00, v113
	v_add_f32_e32 v157, 1.0, v157
	v_log_f32_e32 v241, v157
	v_max_f32_e32 v243, 0, v227
	v_mul_f32_e64 v157, |v227|, s51
	v_exp_f32_e32 v157, v157
	s_nop 0
	v_add_f32_e32 v157, 1.0, v157
	v_log_f32_e32 v245, v157
	v_mov_b32_e32 v157, v115
	s_nop 1
	v_permlane16_swap_b32_e32 v157, v159
	v_cndmask_b32_e64 v157, v157, v159, s[8:9]
	v_mov_b32_e32 v159, v149
	v_add_f32_e32 v157, v115, v157
	s_nop 0
	v_permlane16_swap_b32_e32 v159, v161
	v_cndmask_b32_e64 v159, v159, v161, s[8:9]
	v_mov_b32_e32 v161, v157
	v_mov_b32_e32 v163, v157
	v_add_f32_e32 v159, v149, v159
	s_nop 0
	v_permlane32_swap_b32_e32 v161, v163
	v_cndmask_b32_e64 v161, v161, v163, s[6:7]
	v_mov_b32_e32 v163, v159
	v_mov_b32_e32 v165, v159
	s_nop 1
	v_permlane32_swap_b32_e32 v163, v165
	v_cndmask_b32_e64 v163, v163, v165, s[6:7]
	v_add_f32_e32 v246, v159, v163
	v_sub_f32_e32 v159, v159, v149
	v_fma_f32 v159, v208, v159, v170
	v_fmac_f32_e32 v159, v209, v163
	v_add_f32_e32 v163, v170, v246
	v_sub_f32_e32 v165, v157, v115
	v_fmac_f32_e32 v163, v208, v165
	v_fmac_f32_e32 v163, v209, v161
	v_add_f32_e32 v165, v172, v159
	v_add_f32_e32 v149, v149, v165
	v_add_f32_e32 v165, v232, v163
	v_add_f32_e32 v115, v115, v165
	v_add_f32_e32 v165, v173, v159
	v_add_f32_e32 v151, v151, v165
	v_add_f32_e32 v165, v233, v163
	v_add_f32_e32 v132, v132, v165
	v_add_f32_e32 v165, v174, v159
	v_add_f32_e32 v159, v175, v159
	v_pk_fma_f32 v[174:175], v[228:229], s[62:63], v[176:177] op_sel_hi:[1,0,1]
	v_pk_fma_f32 v[176:177], v[236:237], s[62:63], v[230:231] op_sel_hi:[1,0,1]
	v_pk_fma_f32 v[228:229], v[240:241], s[62:63], v[238:239] op_sel_hi:[1,0,1]
	v_pk_fma_f32 v[230:231], v[244:245], s[62:63], v[242:243] op_sel_hi:[1,0,1]
	v_sub_f32_e32 v155, v159, v155
	v_pk_add_f32 v[228:229], v[228:229], v[230:231] neg_lo:[1,1] neg_hi:[1,1]
	v_add_f32_e32 v159, v235, v163
	v_pk_add_f32 v[176:177], v[228:229], v[176:177] neg_lo:[0,1] neg_hi:[0,1]
	v_add_f32_e32 v153, v153, v165
	v_pk_add_f32 v[174:175], v[176:177], v[174:175] neg_lo:[0,1] neg_hi:[0,1]
	v_add_f32_e32 v165, v234, v163
	v_sub_f32_e32 v143, v159, v143
	v_add_f32_e32 v172, v157, v161
	v_mov_b32_e32 v157, v174
	v_mov_b32_e32 v159, v174
	v_mov_b32_e32 v161, v175
	v_mov_b32_e32 v163, v175
	v_permlane16_swap_b32_e32 v157, v159
	s_nop 0
	v_permlane16_swap_b32_e32 v161, v163
	v_cndmask_b32_e64 v233, v161, v163, s[8:9]
	v_cndmask_b32_e64 v232, v157, v159, s[8:9]
	v_pk_add_f32 v[232:233], v[174:175], v[232:233]
	v_add_f32_e32 v141, v141, v165
	v_mov_b32_e32 v157, v232
	v_mov_b32_e32 v159, v232
	v_mov_b32_e32 v161, v233
	v_mov_b32_e32 v163, v233
	v_permlane32_swap_b32_e32 v157, v159
	s_nop 0
	v_permlane32_swap_b32_e32 v161, v163
	v_cndmask_b32_e64 v235, v161, v163, s[6:7]
	v_cndmask_b32_e64 v234, v157, v159, s[6:7]
	v_pk_add_f32 v[236:237], v[232:233], v[174:175] neg_lo:[0,1] neg_hi:[0,1]
	v_pk_add_f32 v[232:233], v[232:233], v[234:235]
	v_fma_f32 v157, v208, v237, v171
	v_add_f32_e32 v159, v171, v233
	v_fmac_f32_e32 v159, v208, v236
	v_fmac_f32_e32 v159, v209, v234
	v_add_f32_e32 v116, v116, v159
	v_add_f32_e32 v116, v174, v116
	v_fmac_f32_e32 v157, v209, v235
	v_mul_f32_e32 v116, 0x3fb8aa3b, v116
	v_exp_f32_e32 v163, v116
	v_add_f32_e32 v116, v225, v157
	v_add_f32_e32 v116, v177, v116
	v_mul_f32_e32 v116, 0x3fb8aa3b, v116
	v_exp_f32_e32 v165, v116
	v_add_f32_e32 v116, v117, v159
	v_add_f32_e32 v116, v176, v116
	v_mul_f32_e32 v116, 0x3fb8aa3b, v116
	v_exp_f32_e32 v167, v116
	v_add_f32_e32 v116, v226, v157
	v_add_f32_e32 v116, v229, v116
	v_mul_f32_e32 v116, 0x3fb8aa3b, v116
	v_exp_f32_e32 v169, v116
	v_add_f32_e32 v116, v118, v159
	v_add_f32_e32 v116, v228, v116
	v_mul_f32_e32 v116, 0x3fb8aa3b, v116
	v_exp_f32_e32 v174, v116
	v_add_f32_e32 v116, v227, v157
	v_sub_f32_e32 v116, v116, v231
	v_mul_f32_e32 v116, 0x3fb8aa3b, v116
	v_add_f32_e32 v161, v224, v157
	v_exp_f32_e32 v157, v116
	v_add_f32_e32 v116, v119, v159
	v_add_f32_e32 v161, v175, v161
	v_sub_f32_e32 v116, v116, v230
	v_mul_f32_e32 v149, 0x3fb8aa3b, v149
	v_mul_f32_e32 v115, 0x3fb8aa3b, v115
	v_mul_f32_e32 v151, 0x3fb8aa3b, v151
	v_mul_f32_e32 v132, 0x3fb8aa3b, v132
	v_mul_f32_e32 v153, 0x3fb8aa3b, v153
	v_mul_f32_e32 v141, 0x3fb8aa3b, v141
	v_mul_f32_e32 v155, 0x3fb8aa3b, v155
	v_mul_f32_e32 v143, 0x3fb8aa3b, v143
	v_mul_f32_e32 v161, 0x3fb8aa3b, v161
	v_mul_f32_e32 v116, 0x3fb8aa3b, v116
	v_exp_f32_e32 v149, v149
	v_exp_f32_e32 v115, v115
	v_exp_f32_e32 v151, v151
	v_exp_f32_e32 v132, v132
	v_exp_f32_e32 v153, v153
	v_exp_f32_e32 v141, v141
	v_exp_f32_e32 v155, v155
	v_exp_f32_e32 v143, v143
	v_exp_f32_e32 v161, v161
	v_exp_f32_e32 v159, v116
	v_mov_b32_e32 v173, v232
	v_mov_b32_e32 v247, v233
	v_pk_add_f32 v[116:117], v[172:173], v[246:247]
	v_cvt_pk_bf16_f32 v118, v149, v151
	v_pk_add_f32 v[170:171], v[170:171], v[116:117]
	v_cvt_pk_bf16_f32 v116, v115, v132
	v_cmp_gt_f32_e32 vcc, s63, v170
	v_cmp_gt_f32_e64 s[0:1], s63, v171
	v_cvt_pk_bf16_f32 v117, v141, v143
	v_cvt_pk_bf16_f32 v119, v153, v155
	v_cvt_pk_bf16_f32 v172, v163, v167
	v_cvt_pk_bf16_f32 v173, v174, v159
	v_cvt_pk_bf16_f32 v174, v161, v165
	v_cvt_pk_bf16_f32 v175, v169, v157
	s_and_b64 s[0:1], vcc, s[0:1]
	s_waitcnt lgkmcnt(4)
	v_mfma_f32_16x16x32_bf16 v[88:91], v[96:99], v[116:119], v[88:91]
	v_mfma_f32_16x16x32_bf16 v[72:75], v[96:99], v[172:175], v[72:75]
	v_cndmask_b32_e64 v96, 0, 1, s[0:1]
	v_cmp_ne_u32_e32 vcc, 0, v96
	s_cmp_eq_u64 vcc, exec
	s_cselect_b64 s[0:1], -1, 0
	v_cmp_ge_i32_e32 vcc, s22, v112
	s_or_b64 s[20:21], s[0:1], vcc
	v_mfma_f32_16x16x32_bf16 v[92:95], v[100:103], v[116:119], v[92:95]
	s_and_b64 s[20:21], exec, s[20:21]
	s_or_b64 s[16:17], s[20:21], s[16:17]
	s_andn2_b64 s[18:19], s[18:19], exec
	v_mfma_f32_16x16x32_bf16 v[76:79], v[100:103], v[172:175], v[76:79]
	s_and_b64 s[0:1], s[0:1], exec
	v_subrev_u32_e32 v112, 32, v112
	s_or_b64 s[18:19], s[18:19], s[0:1]
	s_waitcnt lgkmcnt(2)
	v_mfma_f32_16x16x32_bf16 v[84:87], v[104:107], v[116:119], v[84:87]
	v_mfma_f32_16x16x32_bf16 v[68:71], v[104:107], v[172:175], v[68:71]
	s_waitcnt lgkmcnt(0)
	ds_read_b128 v[248:251], v113
	v_mfma_f32_16x16x32_bf16 v[80:83], v[108:111], v[116:119], v[80:83]
	v_mfma_f32_16x16x32_bf16 v[64:67], v[108:111], v[172:175], v[64:67]
	s_andn2_b64 exec, exec, s[16:17]
	s_cbranch_execnz .LBB0_229
	s_or_b64 exec, exec, s[16:17]
	s_and_b64 s[0:1], s[18:19], exec
